# GU 8-phase GEMM: next tile's first K-stage LDS-DMA loads issued during the last K step (tail), load-free header for later tiles
# speedup vs baseline: 1.0030x; 1.0030x over previous
.LBB0_122:
	s_or_b64 exec, exec, s[48:49]
	v_mul_f32_e32 v151, 0xbfb8aa3b, v124
	v_exp_f32_e32 v151, v151
	v_or_b32_e32 v130, s44, v133
	v_ashrrev_i32_e32 v130, 1, v130
	v_or_b32_e32 v130, v130, v134
	v_add_f32_e32 v151, 1.0, v151
	v_rcp_f32_e32 v152, v151
	v_mul_f32_e32 v151, 0xbfb8aa3b, v125
	v_exp_f32_e32 v151, v151
	v_ashrrev_i32_e32 v131, 31, v130
	v_add_u32_e32 v150, s42, v135
	v_lshl_add_u64 v[130:131], v[130:131], 1, s[92:93]
	v_add_f32_e32 v151, 1.0, v151
	v_rcp_f32_e32 v153, v151
	v_readlane_b32 s4, v252, 33
	s_add_i32 s76, s76, s4
	s_cmpk_lt_i32 s76, 0xfc
	v_pk_mul_f32 v[124:125], v[124:125], v[152:153]
	s_nop 0
	v_pk_mul_f32 v[120:121], v[120:121], v[124:125]
	s_nop 0
	v_cvt_pk_bf16_f32 v124, v120, v121
	v_mul_f32_e32 v120, 0xbfb8aa3b, v126
	v_mul_f32_e32 v121, 0xbfb8aa3b, v127
	v_exp_f32_e32 v120, v120
	v_exp_f32_e32 v121, v121
	v_add_f32_e32 v120, 1.0, v120
	v_add_f32_e32 v121, 1.0, v121
	v_rcp_f32_e32 v120, v120
	v_rcp_f32_e32 v121, v121
	s_nop 0
	v_pk_mul_f32 v[120:121], v[126:127], v[120:121]
	s_nop 0
	v_pk_mul_f32 v[120:121], v[122:123], v[120:121]
	v_mul_f32_e32 v122, 0xbfb8aa3b, v116
	v_mul_f32_e32 v123, 0xbfb8aa3b, v117
	v_exp_f32_e32 v122, v122
	v_exp_f32_e32 v123, v123
	v_cvt_pk_bf16_f32 v125, v120, v121
	v_mad_i64_i32 v[120:121], s[22:23], v150, s28, v[130:131]
	v_add_f32_e32 v122, 1.0, v122
	v_add_f32_e32 v123, 1.0, v123
	v_rcp_f32_e32 v122, v122
	v_rcp_f32_e32 v123, v123
	global_store_dwordx2 v[120:121], v[124:125], off
	v_pk_mul_f32 v[116:117], v[116:117], v[122:123]
	s_nop 0
	v_pk_mul_f32 v[112:113], v[112:113], v[116:117]
	s_nop 0
	v_cvt_pk_bf16_f32 v116, v112, v113
	v_mul_f32_e32 v112, 0xbfb8aa3b, v118
	v_mul_f32_e32 v113, 0xbfb8aa3b, v119
	v_exp_f32_e32 v112, v112
	v_exp_f32_e32 v113, v113
	v_add_f32_e32 v112, 1.0, v112
	v_add_f32_e32 v113, 1.0, v113
	v_rcp_f32_e32 v112, v112
	v_rcp_f32_e32 v113, v113
	s_nop 0
	v_pk_mul_f32 v[112:113], v[118:119], v[112:113]
	s_nop 0
	v_pk_mul_f32 v[112:113], v[114:115], v[112:113]
	v_mul_f32_e32 v114, 0xbfb8aa3b, v108
	v_mul_f32_e32 v115, 0xbfb8aa3b, v109
	v_exp_f32_e32 v114, v114
	v_exp_f32_e32 v115, v115
	v_cvt_pk_bf16_f32 v117, v112, v113
	v_or_b32_e32 v112, 16, v150
	v_add_f32_e32 v114, 1.0, v114
	v_add_f32_e32 v115, 1.0, v115
	v_rcp_f32_e32 v114, v114
	v_rcp_f32_e32 v115, v115
	v_mad_i64_i32 v[112:113], s[22:23], v112, s28, v[130:131]
	global_store_dwordx2 v[112:113], v[116:117], off
	v_pk_mul_f32 v[108:109], v[108:109], v[114:115]
	s_nop 0
	v_pk_mul_f32 v[104:105], v[104:105], v[108:109]
	s_nop 0
	v_cvt_pk_bf16_f32 v108, v104, v105
	v_mul_f32_e32 v104, 0xbfb8aa3b, v110
	v_mul_f32_e32 v105, 0xbfb8aa3b, v111
	v_exp_f32_e32 v104, v104
	v_exp_f32_e32 v105, v105
	v_add_f32_e32 v104, 1.0, v104
	v_add_f32_e32 v105, 1.0, v105
	v_rcp_f32_e32 v104, v104
	v_rcp_f32_e32 v105, v105
	s_nop 0
	v_pk_mul_f32 v[104:105], v[110:111], v[104:105]
	s_nop 0
	v_pk_mul_f32 v[104:105], v[106:107], v[104:105]
	v_mul_f32_e32 v106, 0xbfb8aa3b, v100
	v_mul_f32_e32 v107, 0xbfb8aa3b, v101
	v_exp_f32_e32 v106, v106
	v_exp_f32_e32 v107, v107
	v_cvt_pk_bf16_f32 v109, v104, v105
	v_or_b32_e32 v104, 32, v150
	v_add_f32_e32 v106, 1.0, v106
	v_add_f32_e32 v107, 1.0, v107
	v_rcp_f32_e32 v106, v106
	v_rcp_f32_e32 v107, v107
	v_mad_i64_i32 v[104:105], s[22:23], v104, s28, v[130:131]
	global_store_dwordx2 v[104:105], v[108:109], off
	v_pk_mul_f32 v[100:101], v[100:101], v[106:107]
	s_nop 0
	v_pk_mul_f32 v[96:97], v[96:97], v[100:101]
	s_nop 0
	v_cvt_pk_bf16_f32 v100, v96, v97
	v_mul_f32_e32 v96, 0xbfb8aa3b, v102
	v_mul_f32_e32 v97, 0xbfb8aa3b, v103
	v_exp_f32_e32 v96, v96
	v_exp_f32_e32 v97, v97
	v_add_f32_e32 v96, 1.0, v96
	v_add_f32_e32 v97, 1.0, v97
	v_rcp_f32_e32 v96, v96
	v_rcp_f32_e32 v97, v97
	s_nop 0
	v_pk_mul_f32 v[96:97], v[102:103], v[96:97]
	s_nop 0
	v_pk_mul_f32 v[96:97], v[98:99], v[96:97]
	v_mul_f32_e32 v98, 0xbfb8aa3b, v92
	v_mul_f32_e32 v99, 0xbfb8aa3b, v93
	v_exp_f32_e32 v98, v98
	v_exp_f32_e32 v99, v99
	v_cvt_pk_bf16_f32 v101, v96, v97
	v_or_b32_e32 v96, 48, v150
	v_add_f32_e32 v98, 1.0, v98
	v_add_f32_e32 v99, 1.0, v99
	v_rcp_f32_e32 v98, v98
	v_rcp_f32_e32 v99, v99
	v_mad_i64_i32 v[96:97], s[22:23], v96, s28, v[130:131]
	global_store_dwordx2 v[96:97], v[100:101], off
	v_pk_mul_f32 v[92:93], v[92:93], v[98:99]
	s_nop 0
	v_pk_mul_f32 v[88:89], v[88:89], v[92:93]
	s_nop 0
	v_cvt_pk_bf16_f32 v88, v88, v89
	v_mul_f32_e32 v89, 0xbfb8aa3b, v94
	v_exp_f32_e32 v89, v89
	s_nop 0
	v_add_f32_e32 v89, 1.0, v89
	v_rcp_f32_e32 v92, v89
	v_mul_f32_e32 v89, 0xbfb8aa3b, v95
	v_exp_f32_e32 v89, v89
	s_nop 0
	v_add_f32_e32 v89, 1.0, v89
	v_rcp_f32_e32 v93, v89
	s_nop 0
	v_pk_mul_f32 v[92:93], v[94:95], v[92:93]
	s_nop 0
	v_pk_mul_f32 v[90:91], v[90:91], v[92:93]
	s_nop 0
	v_cvt_pk_bf16_f32 v89, v90, v91
	global_store_dwordx2 v[120:121], v[88:89], off offset:128
	v_mul_f32_e32 v88, 0xbfb8aa3b, v84
	v_mul_f32_e32 v89, 0xbfb8aa3b, v85
	v_exp_f32_e32 v88, v88
	v_exp_f32_e32 v89, v89
	v_add_f32_e32 v88, 1.0, v88
	v_add_f32_e32 v89, 1.0, v89
	v_rcp_f32_e32 v88, v88
	v_rcp_f32_e32 v89, v89
	s_nop 0
	v_pk_mul_f32 v[84:85], v[84:85], v[88:89]
	s_nop 0
	v_pk_mul_f32 v[80:81], v[80:81], v[84:85]
	s_nop 0
	v_cvt_pk_bf16_f32 v80, v80, v81
	v_mul_f32_e32 v81, 0xbfb8aa3b, v86
	v_exp_f32_e32 v81, v81
	s_nop 0
	v_add_f32_e32 v81, 1.0, v81
	v_rcp_f32_e32 v84, v81
	v_mul_f32_e32 v81, 0xbfb8aa3b, v87
	v_exp_f32_e32 v81, v81
	s_nop 0
	v_add_f32_e32 v81, 1.0, v81
	v_rcp_f32_e32 v85, v81
	s_nop 0
	v_pk_mul_f32 v[84:85], v[86:87], v[84:85]
	s_nop 0
	v_pk_mul_f32 v[82:83], v[82:83], v[84:85]
	s_nop 0
	v_cvt_pk_bf16_f32 v81, v82, v83
	global_store_dwordx2 v[112:113], v[80:81], off offset:128
	v_mul_f32_e32 v80, 0xbfb8aa3b, v76
	v_mul_f32_e32 v81, 0xbfb8aa3b, v77
	v_exp_f32_e32 v80, v80
	v_exp_f32_e32 v81, v81
	v_add_f32_e32 v80, 1.0, v80
	v_add_f32_e32 v81, 1.0, v81
	v_rcp_f32_e32 v80, v80
	v_rcp_f32_e32 v81, v81
	s_nop 0
	v_pk_mul_f32 v[76:77], v[76:77], v[80:81]
	s_nop 0
	v_pk_mul_f32 v[72:73], v[72:73], v[76:77]
	s_nop 0
	v_cvt_pk_bf16_f32 v72, v72, v73
	v_mul_f32_e32 v73, 0xbfb8aa3b, v78
	v_exp_f32_e32 v73, v73
	s_nop 0
	v_add_f32_e32 v73, 1.0, v73
	v_rcp_f32_e32 v76, v73
	v_mul_f32_e32 v73, 0xbfb8aa3b, v79
	v_exp_f32_e32 v73, v73
	s_nop 0
	v_add_f32_e32 v73, 1.0, v73
	v_rcp_f32_e32 v77, v73
	s_nop 0
	v_pk_mul_f32 v[76:77], v[78:79], v[76:77]
	s_nop 0
	v_pk_mul_f32 v[74:75], v[74:75], v[76:77]
	s_nop 0
	v_cvt_pk_bf16_f32 v73, v74, v75
	global_store_dwordx2 v[104:105], v[72:73], off offset:128
	v_mul_f32_e32 v72, 0xbfb8aa3b, v68
	v_mul_f32_e32 v73, 0xbfb8aa3b, v69
	v_exp_f32_e32 v72, v72
	v_exp_f32_e32 v73, v73
	v_add_f32_e32 v72, 1.0, v72
	v_add_f32_e32 v73, 1.0, v73
	v_rcp_f32_e32 v72, v72
	v_rcp_f32_e32 v73, v73
	s_nop 0
	v_pk_mul_f32 v[68:69], v[68:69], v[72:73]
	s_nop 0
	v_pk_mul_f32 v[64:65], v[64:65], v[68:69]
	s_nop 0
	v_cvt_pk_bf16_f32 v64, v64, v65
	v_mul_f32_e32 v65, 0xbfb8aa3b, v70
	v_exp_f32_e32 v65, v65
	s_nop 0
	v_add_f32_e32 v65, 1.0, v65
	v_rcp_f32_e32 v68, v65
	v_mul_f32_e32 v65, 0xbfb8aa3b, v71
	v_exp_f32_e32 v65, v65
	s_nop 0
	v_add_f32_e32 v65, 1.0, v65
	v_rcp_f32_e32 v69, v65
	s_nop 0
	v_pk_mul_f32 v[68:69], v[70:71], v[68:69]
	s_nop 0
	v_pk_mul_f32 v[66:67], v[66:67], v[68:69]
	s_nop 0
	v_cvt_pk_bf16_f32 v65, v66, v67
	global_store_dwordx2 v[96:97], v[64:65], off offset:128
	v_mul_f32_e32 v64, 0xbfb8aa3b, v60
	v_mul_f32_e32 v65, 0xbfb8aa3b, v61
	v_exp_f32_e32 v64, v64
	v_exp_f32_e32 v65, v65
	v_add_u32_e32 v66, 0x80, v150
	v_add_f32_e32 v64, 1.0, v64
	v_add_f32_e32 v65, 1.0, v65
	v_rcp_f32_e32 v64, v64
	v_rcp_f32_e32 v65, v65
	s_nop 0
	v_pk_mul_f32 v[60:61], v[60:61], v[64:65]
	s_nop 0
	v_pk_mul_f32 v[56:57], v[56:57], v[60:61]
	s_nop 0
	v_cvt_pk_bf16_f32 v60, v56, v57
	v_mul_f32_e32 v56, 0xbfb8aa3b, v62
	v_mul_f32_e32 v57, 0xbfb8aa3b, v63
	v_exp_f32_e32 v56, v56
	v_exp_f32_e32 v57, v57
	v_add_f32_e32 v56, 1.0, v56
	v_add_f32_e32 v57, 1.0, v57
	v_rcp_f32_e32 v56, v56
	v_rcp_f32_e32 v57, v57
	s_nop 0
	v_pk_mul_f32 v[56:57], v[62:63], v[56:57]
	s_nop 0
	v_pk_mul_f32 v[56:57], v[58:59], v[56:57]
	v_mul_f32_e32 v58, 0xbfb8aa3b, v52
	v_mul_f32_e32 v59, 0xbfb8aa3b, v53
	v_exp_f32_e32 v58, v58
	v_exp_f32_e32 v59, v59
	v_cvt_pk_bf16_f32 v61, v56, v57
	v_mad_i64_i32 v[56:57], s[22:23], v66, s28, v[130:131]
	v_add_f32_e32 v58, 1.0, v58
	v_add_f32_e32 v59, 1.0, v59
	v_rcp_f32_e32 v58, v58
	v_rcp_f32_e32 v59, v59
	global_store_dwordx2 v[56:57], v[60:61], off
	v_pk_mul_f32 v[52:53], v[52:53], v[58:59]
	s_nop 0
	v_pk_mul_f32 v[48:49], v[48:49], v[52:53]
	s_nop 0
	v_cvt_pk_bf16_f32 v52, v48, v49
	v_mul_f32_e32 v48, 0xbfb8aa3b, v54
	v_mul_f32_e32 v49, 0xbfb8aa3b, v55
	v_exp_f32_e32 v48, v48
	v_exp_f32_e32 v49, v49
	v_add_f32_e32 v48, 1.0, v48
	v_add_f32_e32 v49, 1.0, v49
	v_rcp_f32_e32 v48, v48
	v_rcp_f32_e32 v49, v49
	s_nop 0
	v_pk_mul_f32 v[48:49], v[54:55], v[48:49]
	s_nop 0
	v_pk_mul_f32 v[48:49], v[50:51], v[48:49]
	v_mul_f32_e32 v50, 0xbfb8aa3b, v44
	v_mul_f32_e32 v51, 0xbfb8aa3b, v45
	v_exp_f32_e32 v50, v50
	v_exp_f32_e32 v51, v51
	v_cvt_pk_bf16_f32 v53, v48, v49
	v_add_u32_e32 v48, 0x90, v150
	v_add_f32_e32 v50, 1.0, v50
	v_add_f32_e32 v51, 1.0, v51
	v_rcp_f32_e32 v50, v50
	v_rcp_f32_e32 v51, v51
	v_mad_i64_i32 v[48:49], s[22:23], v48, s28, v[130:131]
	global_store_dwordx2 v[48:49], v[52:53], off
	v_pk_mul_f32 v[44:45], v[44:45], v[50:51]
	s_nop 0
	v_pk_mul_f32 v[40:41], v[40:41], v[44:45]
	s_nop 0
	v_cvt_pk_bf16_f32 v44, v40, v41
	v_mul_f32_e32 v40, 0xbfb8aa3b, v46
	v_mul_f32_e32 v41, 0xbfb8aa3b, v47
	v_exp_f32_e32 v40, v40
	v_exp_f32_e32 v41, v41
	v_add_f32_e32 v40, 1.0, v40
	v_add_f32_e32 v41, 1.0, v41
	v_rcp_f32_e32 v40, v40
	v_rcp_f32_e32 v41, v41
	s_nop 0
	v_pk_mul_f32 v[40:41], v[46:47], v[40:41]
	s_nop 0
	v_pk_mul_f32 v[40:41], v[42:43], v[40:41]
	v_mul_f32_e32 v42, 0xbfb8aa3b, v36
	v_mul_f32_e32 v43, 0xbfb8aa3b, v37
	v_exp_f32_e32 v42, v42
	v_exp_f32_e32 v43, v43
	v_cvt_pk_bf16_f32 v45, v40, v41
	v_add_u32_e32 v40, 0xa0, v150
	v_add_f32_e32 v42, 1.0, v42
	v_add_f32_e32 v43, 1.0, v43
	v_rcp_f32_e32 v42, v42
	v_rcp_f32_e32 v43, v43
	v_mad_i64_i32 v[40:41], s[22:23], v40, s28, v[130:131]
	global_store_dwordx2 v[40:41], v[44:45], off
	v_pk_mul_f32 v[36:37], v[36:37], v[42:43]
	s_nop 0
	v_pk_mul_f32 v[32:33], v[32:33], v[36:37]
	s_nop 0
	v_cvt_pk_bf16_f32 v36, v32, v33
	v_mul_f32_e32 v32, 0xbfb8aa3b, v38
	v_mul_f32_e32 v33, 0xbfb8aa3b, v39
	v_exp_f32_e32 v32, v32
	v_exp_f32_e32 v33, v33
	v_add_f32_e32 v32, 1.0, v32
	v_add_f32_e32 v33, 1.0, v33
	v_rcp_f32_e32 v32, v32
	v_rcp_f32_e32 v33, v33
	s_nop 0
	v_pk_mul_f32 v[32:33], v[38:39], v[32:33]
	s_nop 0
	v_pk_mul_f32 v[32:33], v[34:35], v[32:33]
	v_mul_f32_e32 v34, 0xbfb8aa3b, v28
	v_mul_f32_e32 v35, 0xbfb8aa3b, v29
	v_exp_f32_e32 v34, v34
	v_exp_f32_e32 v35, v35
	v_cvt_pk_bf16_f32 v37, v32, v33
	v_add_u32_e32 v32, 0xb0, v150
	v_add_f32_e32 v34, 1.0, v34
	v_add_f32_e32 v35, 1.0, v35
	v_rcp_f32_e32 v34, v34
	v_rcp_f32_e32 v35, v35
	v_mad_i64_i32 v[32:33], s[22:23], v32, s28, v[130:131]
	global_store_dwordx2 v[32:33], v[36:37], off
	v_pk_mul_f32 v[28:29], v[28:29], v[34:35]
	s_nop 0
	v_pk_mul_f32 v[24:25], v[24:25], v[28:29]
	s_nop 0
	v_cvt_pk_bf16_f32 v24, v24, v25
	v_mul_f32_e32 v25, 0xbfb8aa3b, v30
	v_exp_f32_e32 v25, v25
	s_nop 0
	v_add_f32_e32 v25, 1.0, v25
	v_rcp_f32_e32 v28, v25
	v_mul_f32_e32 v25, 0xbfb8aa3b, v31
	v_exp_f32_e32 v25, v25
	s_nop 0
	v_add_f32_e32 v25, 1.0, v25
	v_rcp_f32_e32 v29, v25
	s_nop 0
	v_pk_mul_f32 v[28:29], v[30:31], v[28:29]
	s_nop 0
	v_pk_mul_f32 v[26:27], v[26:27], v[28:29]
	s_nop 0
	v_cvt_pk_bf16_f32 v25, v26, v27
	global_store_dwordx2 v[56:57], v[24:25], off offset:128
	v_mul_f32_e32 v24, 0xbfb8aa3b, v20
	v_mul_f32_e32 v25, 0xbfb8aa3b, v21
	v_exp_f32_e32 v24, v24
	v_exp_f32_e32 v25, v25
	v_add_f32_e32 v24, 1.0, v24
	v_add_f32_e32 v25, 1.0, v25
	v_rcp_f32_e32 v24, v24
	v_rcp_f32_e32 v25, v25
	s_nop 0
	v_pk_mul_f32 v[20:21], v[20:21], v[24:25]
	s_nop 0
	v_pk_mul_f32 v[16:17], v[16:17], v[20:21]
	s_nop 0
	v_cvt_pk_bf16_f32 v16, v16, v17
	v_mul_f32_e32 v17, 0xbfb8aa3b, v22
	v_exp_f32_e32 v17, v17
	s_nop 0
	v_add_f32_e32 v17, 1.0, v17
	v_rcp_f32_e32 v20, v17
	v_mul_f32_e32 v17, 0xbfb8aa3b, v23
	v_exp_f32_e32 v17, v17
	s_nop 0
	v_add_f32_e32 v17, 1.0, v17
	v_rcp_f32_e32 v21, v17
	s_nop 0
	v_pk_mul_f32 v[20:21], v[22:23], v[20:21]
	s_nop 0
	v_pk_mul_f32 v[18:19], v[18:19], v[20:21]
	s_nop 0
	v_cvt_pk_bf16_f32 v17, v18, v19
	global_store_dwordx2 v[48:49], v[16:17], off offset:128
	v_mul_f32_e32 v16, 0xbfb8aa3b, v12
	v_mul_f32_e32 v17, 0xbfb8aa3b, v13
	v_exp_f32_e32 v16, v16
	v_exp_f32_e32 v17, v17
	v_add_f32_e32 v16, 1.0, v16
	v_add_f32_e32 v17, 1.0, v17
	v_rcp_f32_e32 v16, v16
	v_rcp_f32_e32 v17, v17
	s_nop 0
	v_pk_mul_f32 v[12:13], v[12:13], v[16:17]
	s_nop 0
	v_pk_mul_f32 v[8:9], v[8:9], v[12:13]
	s_nop 0
	v_cvt_pk_bf16_f32 v8, v8, v9
	v_mul_f32_e32 v9, 0xbfb8aa3b, v14
	v_exp_f32_e32 v9, v9
	s_nop 0
	v_add_f32_e32 v9, 1.0, v9
	v_rcp_f32_e32 v12, v9
	v_mul_f32_e32 v9, 0xbfb8aa3b, v15
	v_exp_f32_e32 v9, v9
	s_nop 0
	v_add_f32_e32 v9, 1.0, v9
	v_rcp_f32_e32 v13, v9
	s_nop 0
	v_pk_mul_f32 v[12:13], v[14:15], v[12:13]
	s_nop 0
	v_pk_mul_f32 v[10:11], v[10:11], v[12:13]
	s_nop 0
	v_cvt_pk_bf16_f32 v9, v10, v11
	global_store_dwordx2 v[40:41], v[8:9], off offset:128
	v_mul_f32_e32 v8, 0xbfb8aa3b, v4
	v_mul_f32_e32 v9, 0xbfb8aa3b, v5
	v_exp_f32_e32 v8, v8
	v_exp_f32_e32 v9, v9
	v_add_f32_e32 v8, 1.0, v8
	v_add_f32_e32 v9, 1.0, v9
	v_rcp_f32_e32 v8, v8
	v_rcp_f32_e32 v9, v9
	s_nop 0
	v_pk_mul_f32 v[4:5], v[4:5], v[8:9]
	s_nop 0
	v_pk_mul_f32 v[0:1], v[0:1], v[4:5]
	s_nop 0
	v_cvt_pk_bf16_f32 v0, v0, v1
	v_mul_f32_e32 v1, 0xbfb8aa3b, v6
	v_exp_f32_e32 v1, v1
	s_nop 0
	v_add_f32_e32 v1, 1.0, v1
	v_rcp_f32_e32 v4, v1
	v_mul_f32_e32 v1, 0xbfb8aa3b, v7
	v_exp_f32_e32 v1, v1
	s_nop 0
	v_add_f32_e32 v1, 1.0, v1
	v_rcp_f32_e32 v5, v1
	s_nop 0
	v_pk_mul_f32 v[4:5], v[6:7], v[4:5]
	s_nop 0
	v_pk_mul_f32 v[2:3], v[2:3], v[4:5]
	s_nop 0
	v_cvt_pk_bf16_f32 v1, v2, v3
	global_store_dwordx2 v[32:33], v[0:1], off offset:128
	s_cbranch_scc0 .LBB0_129
	s_branch .Lgu_hdr2

.Lgu_join:
	v_mov_b32_e32 v1, v0
	v_mov_b32_e32 v2, v0
	v_mov_b32_e32 v3, v0
	v_mov_b32_e32 v4, v0
	v_mov_b32_e32 v5, v0
	v_mov_b32_e32 v6, v0
	v_mov_b32_e32 v7, v0
	v_mov_b32_e32 v8, v0
	v_mov_b32_e32 v9, v0
	v_mov_b32_e32 v10, v0
	v_mov_b32_e32 v11, v0
	v_mov_b32_e32 v12, v0
	v_mov_b32_e32 v13, v0
	v_mov_b32_e32 v14, v0
	v_mov_b32_e32 v15, v0
	v_mov_b32_e32 v16, v0
	v_mov_b32_e32 v17, v0
	v_mov_b32_e32 v18, v0
	v_mov_b32_e32 v19, v0
	v_mov_b32_e32 v20, v0
	v_mov_b32_e32 v21, v0
	v_mov_b32_e32 v22, v0
	v_mov_b32_e32 v23, v0
	v_mov_b32_e32 v24, v0
	v_mov_b32_e32 v25, v0
	v_mov_b32_e32 v26, v0
	v_mov_b32_e32 v27, v0
	v_mov_b32_e32 v28, v0
	v_mov_b32_e32 v29, v0
	v_mov_b32_e32 v30, v0
	v_mov_b32_e32 v31, v0
	v_mov_b32_e32 v32, v0
	v_mov_b32_e32 v33, v0
	v_mov_b32_e32 v34, v0
	v_mov_b32_e32 v35, v0
	v_mov_b32_e32 v36, v0
	v_mov_b32_e32 v37, v0
	v_mov_b32_e32 v38, v0
	v_mov_b32_e32 v39, v0
	v_mov_b32_e32 v40, v0
	v_mov_b32_e32 v41, v0
	v_mov_b32_e32 v42, v0
	v_mov_b32_e32 v43, v0
	v_mov_b32_e32 v44, v0
	v_mov_b32_e32 v45, v0
	v_mov_b32_e32 v46, v0
	v_mov_b32_e32 v47, v0
	v_mov_b32_e32 v48, v0
	v_mov_b32_e32 v49, v0
	v_mov_b32_e32 v50, v0
	v_mov_b32_e32 v51, v0
	v_mov_b32_e32 v52, v0
	v_mov_b32_e32 v53, v0
	v_mov_b32_e32 v54, v0
	v_mov_b32_e32 v55, v0
	v_mov_b32_e32 v56, v0
	v_mov_b32_e32 v57, v0
	v_mov_b32_e32 v58, v0
	v_mov_b32_e32 v59, v0
	v_mov_b32_e32 v60, v0
	v_mov_b32_e32 v61, v0
	v_mov_b32_e32 v62, v0
	v_mov_b32_e32 v63, v0
	v_mov_b32_e32 v64, v0
	v_mov_b32_e32 v65, v0
	v_mov_b32_e32 v66, v0
	v_mov_b32_e32 v67, v0
	v_mov_b32_e32 v68, v0
	v_mov_b32_e32 v69, v0
	v_mov_b32_e32 v70, v0
	v_mov_b32_e32 v71, v0
	v_mov_b32_e32 v72, v0
	v_mov_b32_e32 v73, v0
	v_mov_b32_e32 v74, v0
	v_mov_b32_e32 v75, v0
	v_mov_b32_e32 v76, v0
	v_mov_b32_e32 v77, v0
	v_mov_b32_e32 v78, v0
	v_mov_b32_e32 v79, v0
	v_mov_b32_e32 v80, v0
	v_mov_b32_e32 v81, v0
	v_mov_b32_e32 v82, v0
	v_mov_b32_e32 v83, v0
	v_mov_b32_e32 v84, v0
	v_mov_b32_e32 v85, v0
	v_mov_b32_e32 v86, v0
	v_mov_b32_e32 v87, v0
	v_mov_b32_e32 v88, v0
	v_mov_b32_e32 v89, v0
	v_mov_b32_e32 v90, v0
	v_mov_b32_e32 v91, v0
	v_mov_b32_e32 v92, v0
	v_mov_b32_e32 v93, v0
	v_mov_b32_e32 v94, v0
	v_mov_b32_e32 v95, v0
	v_mov_b32_e32 v96, v0
	v_mov_b32_e32 v97, v0
	v_mov_b32_e32 v98, v0
	v_mov_b32_e32 v99, v0
	v_mov_b32_e32 v100, v0
	v_mov_b32_e32 v101, v0
	v_mov_b32_e32 v102, v0
	v_mov_b32_e32 v103, v0
	v_mov_b32_e32 v104, v0
	v_mov_b32_e32 v105, v0
	v_mov_b32_e32 v106, v0
	v_mov_b32_e32 v107, v0
	v_mov_b32_e32 v108, v0
	v_mov_b32_e32 v109, v0
	v_mov_b32_e32 v110, v0
	v_mov_b32_e32 v111, v0
	v_mov_b32_e32 v112, v0
	v_mov_b32_e32 v113, v0
	v_mov_b32_e32 v114, v0
	v_mov_b32_e32 v115, v0
	v_mov_b32_e32 v116, v0
	v_mov_b32_e32 v117, v0
	v_mov_b32_e32 v118, v0
	v_mov_b32_e32 v119, v0
	v_mov_b32_e32 v120, v0
	v_mov_b32_e32 v121, v0
	v_mov_b32_e32 v122, v0
	v_mov_b32_e32 v123, v0
	v_mov_b32_e32 v124, v0
	v_mov_b32_e32 v125, v0
	v_mov_b32_e32 v126, v0
	v_mov_b32_e32 v127, v0
	s_mov_b64 s[4:5], 0x8440080
	s_mov_b64 s[6:7], 0x8460080
	s_mov_b64 s[8:9], 0x8400100
	s_mov_b64 s[10:11], 0x8420100
	s_mov_b64 s[38:39], 0x8440100
	s_mov_b64 s[16:17], 0x8460100
	s_mov_b64 s[18:19], 0x8400180
	s_barrier
.LBB0_126:
	ds_read_b128 v[166:169], v142
	ds_read_b128 v[170:173], v142 offset:1024
	ds_read_b128 v[194:197], v142 offset:2048
	ds_read_b128 v[198:201], v142 offset:3072
	v_add_u32_e32 v165, 0xc000, v152
	v_lshl_add_u64 v[190:191], s[72:73], 0, v[128:129]
	v_readfirstlane_b32 s23, v165
	v_add_u32_e32 v164, 0xe000, v152
	v_lshl_add_u64 v[234:235], v[190:191], 0, s[4:5]
	s_mov_b32 m0, s23
	v_readfirstlane_b32 s23, v164
	ds_read_b128 v[202:205], v143
	ds_read_b128 v[206:209], v143 offset:1024
	ds_read_b128 v[210:213], v144
	ds_read_b128 v[214:217], v144 offset:1024
	ds_read_b128 v[218:221], v145
	ds_read_b128 v[222:225], v145 offset:1024
	ds_read_b128 v[226:229], v146
	ds_read_b128 v[230:233], v146 offset:1024
	global_load_lds_dwordx4 v[234:235], off
	v_lshl_add_u64 v[234:235], v[190:191], 0, s[6:7]
	s_mov_b32 m0, s23
	s_nop 0
	global_load_lds_dwordx4 v[234:235], off
	s_waitcnt lgkmcnt(8)
	s_barrier
	s_waitcnt lgkmcnt(0)
	s_setprio 1
	s_waitcnt lgkmcnt(0)
	v_mfma_f32_16x16x32_bf16 v[124:127], v[166:169], v[202:205], v[124:127]
	v_mfma_f32_16x16x32_bf16 v[120:123], v[194:197], v[202:205], v[120:123]
	v_mfma_f32_16x16x32_bf16 v[116:119], v[166:169], v[210:213], v[116:119]
	v_mfma_f32_16x16x32_bf16 v[112:115], v[194:197], v[210:213], v[112:115]
	v_mfma_f32_16x16x32_bf16 v[108:111], v[166:169], v[218:221], v[108:111]
	v_mfma_f32_16x16x32_bf16 v[104:107], v[194:197], v[218:221], v[104:107]
	v_mfma_f32_16x16x32_bf16 v[100:103], v[166:169], v[226:229], v[100:103]
	v_mfma_f32_16x16x32_bf16 v[96:99], v[194:197], v[226:229], v[96:99]
	v_mfma_f32_16x16x32_bf16 v[124:127], v[170:173], v[206:209], v[124:127]
	v_mfma_f32_16x16x32_bf16 v[120:123], v[198:201], v[206:209], v[120:123]
	v_mfma_f32_16x16x32_bf16 v[116:119], v[170:173], v[214:217], v[116:119]
	v_mfma_f32_16x16x32_bf16 v[112:115], v[198:201], v[214:217], v[112:115]
	v_mfma_f32_16x16x32_bf16 v[108:111], v[170:173], v[222:225], v[108:111]
	v_mfma_f32_16x16x32_bf16 v[104:107], v[198:201], v[222:225], v[104:107]
	v_mfma_f32_16x16x32_bf16 v[100:103], v[170:173], v[230:233], v[100:103]
	v_mfma_f32_16x16x32_bf16 v[96:99], v[198:201], v[230:233], v[96:99]
	s_setprio 0
	s_barrier
	v_lshl_add_u64 v[192:193], s[70:71], 0, v[128:129]
	s_mov_b64 s[34:35], 0x14bc0100
	v_readfirstlane_b32 s23, v150
	v_lshl_add_u64 v[188:189], v[192:193], 0, s[34:35]
	s_mov_b32 m0, s23
	s_mov_b64 s[34:35], 0x14be0100
	v_readfirstlane_b32 s23, v151
	ds_read_b128 v[234:237], v147
	ds_read_b128 v[238:241], v147 offset:1024
	ds_read_b128 v[242:245], v147 offset:2048
	ds_read_b128 v[246:249], v147 offset:3072
	global_load_lds_dwordx4 v[188:189], off
	v_lshl_add_u64 v[188:189], v[192:193], 0, s[34:35]
	s_mov_b32 m0, s23
	s_nop 0
	global_load_lds_dwordx4 v[188:189], off
	s_barrier
	s_waitcnt lgkmcnt(0)
	s_setprio 1
	s_waitcnt lgkmcnt(0)
	v_mfma_f32_16x16x32_bf16 v[92:95], v[234:237], v[202:205], v[92:95]
	v_mfma_f32_16x16x32_bf16 v[88:91], v[242:245], v[202:205], v[88:91]
	v_mfma_f32_16x16x32_bf16 v[84:87], v[234:237], v[210:213], v[84:87]
	v_mfma_f32_16x16x32_bf16 v[80:83], v[242:245], v[210:213], v[80:83]
	v_mfma_f32_16x16x32_bf16 v[76:79], v[234:237], v[218:221], v[76:79]
	v_mfma_f32_16x16x32_bf16 v[72:75], v[242:245], v[218:221], v[72:75]
	v_mfma_f32_16x16x32_bf16 v[68:71], v[234:237], v[226:229], v[68:71]
	v_mfma_f32_16x16x32_bf16 v[64:67], v[242:245], v[226:229], v[64:67]
	v_mfma_f32_16x16x32_bf16 v[92:95], v[238:241], v[206:209], v[92:95]
	v_mfma_f32_16x16x32_bf16 v[88:91], v[246:249], v[206:209], v[88:91]
	v_mfma_f32_16x16x32_bf16 v[84:87], v[238:241], v[214:217], v[84:87]
	v_mfma_f32_16x16x32_bf16 v[80:83], v[246:249], v[214:217], v[80:83]
	v_mfma_f32_16x16x32_bf16 v[76:79], v[238:241], v[222:225], v[76:79]
	v_mfma_f32_16x16x32_bf16 v[72:75], v[246:249], v[222:225], v[72:75]
	v_mfma_f32_16x16x32_bf16 v[68:71], v[238:241], v[230:233], v[68:71]
	v_mfma_f32_16x16x32_bf16 v[64:67], v[246:249], v[230:233], v[64:67]
	s_setprio 0
	v_readfirstlane_b32 s23, v152
	v_lshl_add_u64 v[188:189], v[190:191], 0, s[8:9]
	s_mov_b32 m0, s23
	v_readfirstlane_b32 s23, v153
	s_barrier
	ds_read_b128 v[202:205], v143 offset:16384
	ds_read_b128 v[206:209], v143 offset:17408
	ds_read_b128 v[210:213], v144 offset:16384
	ds_read_b128 v[214:217], v144 offset:17408
	ds_read_b128 v[218:221], v145 offset:16384
	ds_read_b128 v[222:225], v145 offset:17408
	ds_read_b128 v[226:229], v146 offset:16384
	ds_read_b128 v[230:233], v146 offset:17408
	global_load_lds_dwordx4 v[188:189], off
	v_lshl_add_u64 v[188:189], v[190:191], 0, s[10:11]
	s_mov_b32 m0, s23
	s_nop 0
	global_load_lds_dwordx4 v[188:189], off
	s_barrier
	s_waitcnt lgkmcnt(0)
	s_setprio 1
	s_waitcnt lgkmcnt(0)
	v_mfma_f32_16x16x32_bf16 v[60:63], v[166:169], v[202:205], v[60:63]
	v_mfma_f32_16x16x32_bf16 v[56:59], v[194:197], v[202:205], v[56:59]
	v_mfma_f32_16x16x32_bf16 v[52:55], v[166:169], v[210:213], v[52:55]
	v_mfma_f32_16x16x32_bf16 v[48:51], v[194:197], v[210:213], v[48:51]
	v_mfma_f32_16x16x32_bf16 v[44:47], v[166:169], v[218:221], v[44:47]
	v_mfma_f32_16x16x32_bf16 v[40:43], v[194:197], v[218:221], v[40:43]
	v_mfma_f32_16x16x32_bf16 v[36:39], v[166:169], v[226:229], v[36:39]
	v_mfma_f32_16x16x32_bf16 v[32:35], v[194:197], v[226:229], v[32:35]
	v_mfma_f32_16x16x32_bf16 v[60:63], v[170:173], v[206:209], v[60:63]
	v_mfma_f32_16x16x32_bf16 v[56:59], v[198:201], v[206:209], v[56:59]
	v_mfma_f32_16x16x32_bf16 v[52:55], v[170:173], v[214:217], v[52:55]
	v_mfma_f32_16x16x32_bf16 v[48:51], v[198:201], v[214:217], v[48:51]
	v_mfma_f32_16x16x32_bf16 v[44:47], v[170:173], v[222:225], v[44:47]
	v_mfma_f32_16x16x32_bf16 v[40:43], v[198:201], v[222:225], v[40:43]
	v_mfma_f32_16x16x32_bf16 v[36:39], v[170:173], v[230:233], v[36:39]
	v_mfma_f32_16x16x32_bf16 v[32:35], v[198:201], v[230:233], v[32:35]
	s_setprio 0
	s_barrier
	s_mov_b64 s[34:35], 0x14c00100
	v_readfirstlane_b32 s23, v154
	v_lshl_add_u64 v[166:167], v[192:193], 0, s[34:35]
	s_mov_b32 m0, s23
	s_mov_b64 s[34:35], 0x14c20100
	v_readfirstlane_b32 s23, v155
	global_load_lds_dwordx4 v[166:167], off
	v_lshl_add_u64 v[166:167], v[192:193], 0, s[34:35]
	s_mov_b32 m0, s23
	s_nop 0
	global_load_lds_dwordx4 v[166:167], off
	s_waitcnt vmcnt(6)
	s_barrier
	s_setprio 1
	v_mfma_f32_16x16x32_bf16 v[28:31], v[234:237], v[202:205], v[28:31]
	v_mfma_f32_16x16x32_bf16 v[24:27], v[242:245], v[202:205], v[24:27]
	v_mfma_f32_16x16x32_bf16 v[20:23], v[234:237], v[210:213], v[20:23]
	v_mfma_f32_16x16x32_bf16 v[16:19], v[242:245], v[210:213], v[16:19]
	v_mfma_f32_16x16x32_bf16 v[12:15], v[234:237], v[218:221], v[12:15]
	v_mfma_f32_16x16x32_bf16 v[8:11], v[242:245], v[218:221], v[8:11]
	v_mfma_f32_16x16x32_bf16 v[4:7], v[234:237], v[226:229], v[4:7]
	v_mfma_f32_16x16x32_bf16 v[0:3], v[242:245], v[226:229], v[0:3]
	v_mfma_f32_16x16x32_bf16 v[28:31], v[238:241], v[206:209], v[28:31]
	v_mfma_f32_16x16x32_bf16 v[24:27], v[246:249], v[206:209], v[24:27]
	v_mfma_f32_16x16x32_bf16 v[20:23], v[238:241], v[214:217], v[20:23]
	v_mfma_f32_16x16x32_bf16 v[16:19], v[246:249], v[214:217], v[16:19]
	v_mfma_f32_16x16x32_bf16 v[12:15], v[238:241], v[222:225], v[12:15]
	v_mfma_f32_16x16x32_bf16 v[8:11], v[246:249], v[222:225], v[8:11]
	v_mfma_f32_16x16x32_bf16 v[4:7], v[238:241], v[230:233], v[4:7]
	v_mfma_f32_16x16x32_bf16 v[0:3], v[246:249], v[230:233], v[0:3]
	s_setprio 0
	s_barrier
	ds_read_b128 v[166:169], v148
	ds_read_b128 v[170:173], v148 offset:1024
	ds_read_b128 v[194:197], v148 offset:2048
	ds_read_b128 v[198:201], v148 offset:3072
	v_readfirstlane_b32 s23, v156
	v_lshl_add_u64 v[188:189], v[190:191], 0, s[38:39]
	s_mov_b32 m0, s23
	v_readfirstlane_b32 s23, v157
	ds_read_b128 v[202:205], v143 offset:32768
	ds_read_b128 v[206:209], v143 offset:33792
	ds_read_b128 v[210:213], v144 offset:32768
	ds_read_b128 v[214:217], v144 offset:33792
	ds_read_b128 v[218:221], v145 offset:32768
	ds_read_b128 v[222:225], v145 offset:33792
	ds_read_b128 v[226:229], v146 offset:32768
	ds_read_b128 v[230:233], v146 offset:33792
	global_load_lds_dwordx4 v[188:189], off
	v_lshl_add_u64 v[188:189], v[190:191], 0, s[16:17]
	s_mov_b32 m0, s23
	s_nop 0
	global_load_lds_dwordx4 v[188:189], off
	s_waitcnt lgkmcnt(8)
	s_barrier
	s_waitcnt lgkmcnt(0)
	s_setprio 1
	s_waitcnt lgkmcnt(0)
	v_mfma_f32_16x16x32_bf16 v[124:127], v[166:169], v[202:205], v[124:127]
	v_mfma_f32_16x16x32_bf16 v[120:123], v[194:197], v[202:205], v[120:123]
	v_mfma_f32_16x16x32_bf16 v[116:119], v[166:169], v[210:213], v[116:119]
	v_mfma_f32_16x16x32_bf16 v[112:115], v[194:197], v[210:213], v[112:115]
	v_mfma_f32_16x16x32_bf16 v[108:111], v[166:169], v[218:221], v[108:111]
	v_mfma_f32_16x16x32_bf16 v[104:107], v[194:197], v[218:221], v[104:107]
	v_mfma_f32_16x16x32_bf16 v[100:103], v[166:169], v[226:229], v[100:103]
	v_mfma_f32_16x16x32_bf16 v[96:99], v[194:197], v[226:229], v[96:99]
	v_mfma_f32_16x16x32_bf16 v[124:127], v[170:173], v[206:209], v[124:127]
	v_mfma_f32_16x16x32_bf16 v[120:123], v[198:201], v[206:209], v[120:123]
	v_mfma_f32_16x16x32_bf16 v[116:119], v[170:173], v[214:217], v[116:119]
	v_mfma_f32_16x16x32_bf16 v[112:115], v[198:201], v[214:217], v[112:115]
	v_mfma_f32_16x16x32_bf16 v[108:111], v[170:173], v[222:225], v[108:111]
	v_mfma_f32_16x16x32_bf16 v[104:107], v[198:201], v[222:225], v[104:107]
	v_mfma_f32_16x16x32_bf16 v[100:103], v[170:173], v[230:233], v[100:103]
	v_mfma_f32_16x16x32_bf16 v[96:99], v[198:201], v[230:233], v[96:99]
	s_setprio 0
	s_barrier
	s_mov_b64 s[34:35], 0x14bc0180
	v_readfirstlane_b32 s23, v158
	v_lshl_add_u64 v[188:189], v[192:193], 0, s[34:35]
	s_mov_b32 m0, s23
	s_mov_b64 s[34:35], 0x14be0180
	v_readfirstlane_b32 s23, v159
	ds_read_b128 v[234:237], v149
	ds_read_b128 v[238:241], v149 offset:1024
	ds_read_b128 v[242:245], v149 offset:2048
	ds_read_b128 v[246:249], v149 offset:3072
	global_load_lds_dwordx4 v[188:189], off
	v_lshl_add_u64 v[188:189], v[192:193], 0, s[34:35]
	s_mov_b32 m0, s23
	s_nop 0
	global_load_lds_dwordx4 v[188:189], off
	s_barrier
	s_waitcnt lgkmcnt(0)
	s_setprio 1
	s_waitcnt lgkmcnt(0)
	v_mfma_f32_16x16x32_bf16 v[92:95], v[234:237], v[202:205], v[92:95]
	v_mfma_f32_16x16x32_bf16 v[88:91], v[242:245], v[202:205], v[88:91]
	v_mfma_f32_16x16x32_bf16 v[84:87], v[234:237], v[210:213], v[84:87]
	v_mfma_f32_16x16x32_bf16 v[80:83], v[242:245], v[210:213], v[80:83]
	v_mfma_f32_16x16x32_bf16 v[76:79], v[234:237], v[218:221], v[76:79]
	v_mfma_f32_16x16x32_bf16 v[72:75], v[242:245], v[218:221], v[72:75]
	v_mfma_f32_16x16x32_bf16 v[68:71], v[234:237], v[226:229], v[68:71]
	v_mfma_f32_16x16x32_bf16 v[64:67], v[242:245], v[226:229], v[64:67]
	v_mfma_f32_16x16x32_bf16 v[92:95], v[238:241], v[206:209], v[92:95]
	v_mfma_f32_16x16x32_bf16 v[88:91], v[246:249], v[206:209], v[88:91]
	v_mfma_f32_16x16x32_bf16 v[84:87], v[238:241], v[214:217], v[84:87]
	v_mfma_f32_16x16x32_bf16 v[80:83], v[246:249], v[214:217], v[80:83]
	v_mfma_f32_16x16x32_bf16 v[76:79], v[238:241], v[222:225], v[76:79]
	v_mfma_f32_16x16x32_bf16 v[72:75], v[246:249], v[222:225], v[72:75]
	v_mfma_f32_16x16x32_bf16 v[68:71], v[238:241], v[230:233], v[68:71]
	v_mfma_f32_16x16x32_bf16 v[64:67], v[246:249], v[230:233], v[64:67]
	s_setprio 0
	v_readfirstlane_b32 s23, v160
	v_lshl_add_u64 v[188:189], v[190:191], 0, s[18:19]
	s_mov_b32 m0, s23
	v_readfirstlane_b32 s23, v161
	s_barrier
	ds_read_b128 v[202:205], v143 offset:49152
	ds_read_b128 v[206:209], v143 offset:50176
	ds_read_b128 v[210:213], v144 offset:49152
	ds_read_b128 v[214:217], v144 offset:50176
	ds_read_b128 v[218:221], v145 offset:49152
	ds_read_b128 v[222:225], v145 offset:50176
	ds_read_b128 v[226:229], v146 offset:49152
	ds_read_b128 v[230:233], v146 offset:50176
	global_load_lds_dwordx4 v[188:189], off
	v_lshl_add_u64 v[188:189], v[190:191], 0, s[86:87]
	s_mov_b32 m0, s23
	s_nop 0
	global_load_lds_dwordx4 v[188:189], off
	s_barrier
	s_waitcnt lgkmcnt(0)
	s_setprio 1
	s_waitcnt lgkmcnt(0)
	v_mfma_f32_16x16x32_bf16 v[60:63], v[166:169], v[202:205], v[60:63]
	v_mfma_f32_16x16x32_bf16 v[56:59], v[194:197], v[202:205], v[56:59]
	v_mfma_f32_16x16x32_bf16 v[52:55], v[166:169], v[210:213], v[52:55]
	v_mfma_f32_16x16x32_bf16 v[48:51], v[194:197], v[210:213], v[48:51]
	v_mfma_f32_16x16x32_bf16 v[44:47], v[166:169], v[218:221], v[44:47]
	v_mfma_f32_16x16x32_bf16 v[40:43], v[194:197], v[218:221], v[40:43]
	v_mfma_f32_16x16x32_bf16 v[36:39], v[166:169], v[226:229], v[36:39]
	v_mfma_f32_16x16x32_bf16 v[32:35], v[194:197], v[226:229], v[32:35]
	v_mfma_f32_16x16x32_bf16 v[60:63], v[170:173], v[206:209], v[60:63]
	v_mfma_f32_16x16x32_bf16 v[56:59], v[198:201], v[206:209], v[56:59]
	v_mfma_f32_16x16x32_bf16 v[52:55], v[170:173], v[214:217], v[52:55]
	v_mfma_f32_16x16x32_bf16 v[48:51], v[198:201], v[214:217], v[48:51]
	v_mfma_f32_16x16x32_bf16 v[44:47], v[170:173], v[222:225], v[44:47]
	v_mfma_f32_16x16x32_bf16 v[40:43], v[198:201], v[222:225], v[40:43]
	v_mfma_f32_16x16x32_bf16 v[36:39], v[170:173], v[230:233], v[36:39]
	v_mfma_f32_16x16x32_bf16 v[32:35], v[198:201], v[230:233], v[32:35]
	s_setprio 0
	s_barrier
	s_mov_b64 s[34:35], 0x14c00180
	v_readfirstlane_b32 s23, v162
	v_lshl_add_u64 v[166:167], v[192:193], 0, s[34:35]
	s_mov_b32 m0, s23
	s_mov_b64 s[34:35], 0x14c20180
	v_readfirstlane_b32 s23, v163
	global_load_lds_dwordx4 v[166:167], off
	v_lshl_add_u64 v[166:167], v[192:193], 0, s[34:35]
	s_mov_b32 m0, s23
	s_nop 0
	global_load_lds_dwordx4 v[166:167], off
	s_waitcnt vmcnt(6)
	s_barrier
	s_setprio 1
	v_mfma_f32_16x16x32_bf16 v[28:31], v[234:237], v[202:205], v[28:31]
	v_mfma_f32_16x16x32_bf16 v[24:27], v[242:245], v[202:205], v[24:27]
	v_mfma_f32_16x16x32_bf16 v[20:23], v[234:237], v[210:213], v[20:23]
	v_mfma_f32_16x16x32_bf16 v[16:19], v[242:245], v[210:213], v[16:19]
	v_mfma_f32_16x16x32_bf16 v[12:15], v[234:237], v[218:221], v[12:15]
	v_mfma_f32_16x16x32_bf16 v[8:11], v[242:245], v[218:221], v[8:11]
	v_mfma_f32_16x16x32_bf16 v[4:7], v[234:237], v[226:229], v[4:7]
	v_mfma_f32_16x16x32_bf16 v[0:3], v[242:245], v[226:229], v[0:3]
	v_mfma_f32_16x16x32_bf16 v[28:31], v[238:241], v[206:209], v[28:31]
	v_mfma_f32_16x16x32_bf16 v[24:27], v[246:249], v[206:209], v[24:27]
	v_mfma_f32_16x16x32_bf16 v[20:23], v[238:241], v[214:217], v[20:23]
	v_mfma_f32_16x16x32_bf16 v[16:19], v[246:249], v[214:217], v[16:19]
	v_mfma_f32_16x16x32_bf16 v[12:15], v[238:241], v[222:225], v[12:15]
	v_mfma_f32_16x16x32_bf16 v[8:11], v[246:249], v[222:225], v[8:11]
	v_mfma_f32_16x16x32_bf16 v[4:7], v[238:241], v[230:233], v[4:7]
	v_mfma_f32_16x16x32_bf16 v[0:3], v[246:249], v[230:233], v[0:3]
	s_setprio 0
	s_add_i32 s22, s22, 2
	s_add_u32 s70, s70, 0x100
	s_addc_u32 s71, s71, 0
	s_add_u32 s72, s72, 0x100
	s_addc_u32 s73, s73, 0
	s_cmp_lt_u32 s22, 12
	s_barrier
	s_cbranch_scc1 .LBB0_126
	v_readlane_b32 s34, v252, 33
	s_add_i32 s34, s76, s34
	s_cmpk_lt_i32 s34, 0xfc
	s_cbranch_scc1 .Lgu_tpf
	s_mov_b64 s[4:5], 0x780
	v_readfirstlane_b32 s22, v165
	v_lshl_add_u64 v[130:131], v[130:131], 0, s[4:5]
	s_mov_b32 m0, s22
	ds_read_b128 v[150:153], v142
	ds_read_b128 v[154:157], v142 offset:1024
	ds_read_b128 v[158:161], v142 offset:2048
	ds_read_b128 v[166:169], v142 offset:3072
	ds_read_b128 v[170:173], v143
	ds_read_b128 v[194:197], v143 offset:1024
	ds_read_b128 v[198:201], v144
	ds_read_b128 v[202:205], v144 offset:1024
	ds_read_b128 v[206:209], v145
	ds_read_b128 v[210:213], v145 offset:1024
	ds_read_b128 v[214:217], v146
	ds_read_b128 v[218:221], v146 offset:1024
	global_load_lds_dwordx4 v[130:131], off
	v_lshl_add_u64 v[130:131], v[136:137], 1, s[48:49]
	s_mov_b64 s[4:5], 0x20780
	v_readfirstlane_b32 s22, v164
	v_lshl_add_u64 v[130:131], v[130:131], 0, s[4:5]
	s_mov_b32 m0, s22
	s_nop 0
	global_load_lds_dwordx4 v[130:131], off
	s_barrier
	s_waitcnt lgkmcnt(0)
	s_setprio 1
	s_waitcnt lgkmcnt(0)
	v_mfma_f32_16x16x32_bf16 v[124:127], v[150:153], v[170:173], v[124:127]
	v_mfma_f32_16x16x32_bf16 v[120:123], v[158:161], v[170:173], v[120:123]
	v_mfma_f32_16x16x32_bf16 v[116:119], v[150:153], v[198:201], v[116:119]
	v_mfma_f32_16x16x32_bf16 v[112:115], v[158:161], v[198:201], v[112:115]
	v_mfma_f32_16x16x32_bf16 v[108:111], v[150:153], v[206:209], v[108:111]
	v_mfma_f32_16x16x32_bf16 v[104:107], v[158:161], v[206:209], v[104:107]
	v_mfma_f32_16x16x32_bf16 v[100:103], v[150:153], v[214:217], v[100:103]
	v_mfma_f32_16x16x32_bf16 v[96:99], v[158:161], v[214:217], v[96:99]
	v_mfma_f32_16x16x32_bf16 v[124:127], v[154:157], v[194:197], v[124:127]
	v_mfma_f32_16x16x32_bf16 v[120:123], v[166:169], v[194:197], v[120:123]
	v_mfma_f32_16x16x32_bf16 v[116:119], v[154:157], v[202:205], v[116:119]
	v_mfma_f32_16x16x32_bf16 v[112:115], v[166:169], v[202:205], v[112:115]
	v_mfma_f32_16x16x32_bf16 v[108:111], v[154:157], v[210:213], v[108:111]
	v_mfma_f32_16x16x32_bf16 v[104:107], v[166:169], v[210:213], v[104:107]
	v_mfma_f32_16x16x32_bf16 v[100:103], v[154:157], v[218:221], v[100:103]
	v_mfma_f32_16x16x32_bf16 v[96:99], v[166:169], v[218:221], v[96:99]
	s_setprio 0
	s_barrier
	ds_read_b128 v[162:165], v147
	ds_read_b128 v[222:225], v147 offset:1024
	ds_read_b128 v[226:229], v147 offset:2048
	ds_read_b128 v[230:233], v147 offset:3072
	s_barrier
	s_waitcnt lgkmcnt(0)
	s_setprio 1
	s_waitcnt lgkmcnt(0)
	v_mfma_f32_16x16x32_bf16 v[92:95], v[162:165], v[170:173], v[92:95]
	v_mfma_f32_16x16x32_bf16 v[88:91], v[226:229], v[170:173], v[88:91]
	v_mfma_f32_16x16x32_bf16 v[84:87], v[162:165], v[198:201], v[84:87]
	v_mfma_f32_16x16x32_bf16 v[80:83], v[226:229], v[198:201], v[80:83]
	v_mfma_f32_16x16x32_bf16 v[76:79], v[162:165], v[206:209], v[76:79]
	v_mfma_f32_16x16x32_bf16 v[72:75], v[226:229], v[206:209], v[72:75]
	v_mfma_f32_16x16x32_bf16 v[68:71], v[162:165], v[214:217], v[68:71]
	v_mfma_f32_16x16x32_bf16 v[64:67], v[226:229], v[214:217], v[64:67]
	v_mfma_f32_16x16x32_bf16 v[92:95], v[222:225], v[194:197], v[92:95]
	v_mfma_f32_16x16x32_bf16 v[88:91], v[230:233], v[194:197], v[88:91]
	v_mfma_f32_16x16x32_bf16 v[84:87], v[222:225], v[202:205], v[84:87]
	v_mfma_f32_16x16x32_bf16 v[80:83], v[230:233], v[202:205], v[80:83]
	v_mfma_f32_16x16x32_bf16 v[76:79], v[222:225], v[210:213], v[76:79]
	v_mfma_f32_16x16x32_bf16 v[72:75], v[230:233], v[210:213], v[72:75]
	v_mfma_f32_16x16x32_bf16 v[68:71], v[222:225], v[218:221], v[68:71]
	v_mfma_f32_16x16x32_bf16 v[64:67], v[230:233], v[218:221], v[64:67]
	s_setprio 0
	s_barrier
	ds_read_b128 v[170:173], v143 offset:16384
	ds_read_b128 v[194:197], v143 offset:17408
	ds_read_b128 v[198:201], v144 offset:16384
	ds_read_b128 v[202:205], v144 offset:17408
	ds_read_b128 v[206:209], v145 offset:16384
	ds_read_b128 v[210:213], v145 offset:17408
	ds_read_b128 v[214:217], v146 offset:16384
	ds_read_b128 v[218:221], v146 offset:17408
	s_waitcnt vmcnt(4)
	s_barrier
	s_waitcnt lgkmcnt(0)
	s_setprio 1
	s_waitcnt lgkmcnt(0)
	v_mfma_f32_16x16x32_bf16 v[60:63], v[150:153], v[170:173], v[60:63]
	v_mfma_f32_16x16x32_bf16 v[56:59], v[158:161], v[170:173], v[56:59]
	v_mfma_f32_16x16x32_bf16 v[52:55], v[150:153], v[198:201], v[52:55]
	v_mfma_f32_16x16x32_bf16 v[48:51], v[158:161], v[198:201], v[48:51]
	v_mfma_f32_16x16x32_bf16 v[44:47], v[150:153], v[206:209], v[44:47]
	v_mfma_f32_16x16x32_bf16 v[40:43], v[158:161], v[206:209], v[40:43]
	v_mfma_f32_16x16x32_bf16 v[36:39], v[150:153], v[214:217], v[36:39]
	v_mfma_f32_16x16x32_bf16 v[32:35], v[158:161], v[214:217], v[32:35]
	v_mfma_f32_16x16x32_bf16 v[60:63], v[154:157], v[194:197], v[60:63]
	v_mfma_f32_16x16x32_bf16 v[56:59], v[166:169], v[194:197], v[56:59]
	v_mfma_f32_16x16x32_bf16 v[52:55], v[154:157], v[202:205], v[52:55]
	v_mfma_f32_16x16x32_bf16 v[48:51], v[166:169], v[202:205], v[48:51]
	v_mfma_f32_16x16x32_bf16 v[44:47], v[154:157], v[210:213], v[44:47]
	v_mfma_f32_16x16x32_bf16 v[40:43], v[166:169], v[210:213], v[40:43]
	v_mfma_f32_16x16x32_bf16 v[36:39], v[154:157], v[218:221], v[36:39]
	v_mfma_f32_16x16x32_bf16 v[32:35], v[166:169], v[218:221], v[32:35]
	s_setprio 0
	s_setprio 1
	v_mfma_f32_16x16x32_bf16 v[28:31], v[162:165], v[170:173], v[28:31]
	v_mfma_f32_16x16x32_bf16 v[24:27], v[226:229], v[170:173], v[24:27]
	v_mfma_f32_16x16x32_bf16 v[20:23], v[162:165], v[198:201], v[20:23]
	v_mfma_f32_16x16x32_bf16 v[16:19], v[226:229], v[198:201], v[16:19]
	v_mfma_f32_16x16x32_bf16 v[12:15], v[162:165], v[206:209], v[12:15]
	v_mfma_f32_16x16x32_bf16 v[8:11], v[226:229], v[206:209], v[8:11]
	v_mfma_f32_16x16x32_bf16 v[4:7], v[162:165], v[214:217], v[4:7]
	v_mfma_f32_16x16x32_bf16 v[0:3], v[226:229], v[214:217], v[0:3]
	v_mfma_f32_16x16x32_bf16 v[28:31], v[222:225], v[194:197], v[28:31]
	v_mfma_f32_16x16x32_bf16 v[24:27], v[230:233], v[194:197], v[24:27]
	v_mfma_f32_16x16x32_bf16 v[20:23], v[222:225], v[202:205], v[20:23]
	v_mfma_f32_16x16x32_bf16 v[16:19], v[230:233], v[202:205], v[16:19]
	v_mfma_f32_16x16x32_bf16 v[12:15], v[222:225], v[210:213], v[12:15]
	v_mfma_f32_16x16x32_bf16 v[8:11], v[230:233], v[210:213], v[8:11]
	v_mfma_f32_16x16x32_bf16 v[4:7], v[222:225], v[218:221], v[4:7]
	v_mfma_f32_16x16x32_bf16 v[0:3], v[230:233], v[218:221], v[0:3]
	s_setprio 0
	s_barrier
	ds_read_b128 v[150:153], v148
	ds_read_b128 v[154:157], v148 offset:1024
	ds_read_b128 v[158:161], v148 offset:2048
	ds_read_b128 v[162:165], v148 offset:3072
	ds_read_b128 v[166:169], v143 offset:32768
	ds_read_b128 v[170:173], v143 offset:33792
	ds_read_b128 v[194:197], v144 offset:32768
	ds_read_b128 v[198:201], v144 offset:33792
	ds_read_b128 v[202:205], v145 offset:32768
	ds_read_b128 v[206:209], v145 offset:33792
	ds_read_b128 v[210:213], v146 offset:32768
	ds_read_b128 v[214:217], v146 offset:33792
	s_waitcnt vmcnt(2)
	s_barrier
	s_waitcnt lgkmcnt(0)
	s_setprio 1
	s_waitcnt lgkmcnt(0)
	v_mfma_f32_16x16x32_bf16 v[124:127], v[150:153], v[166:169], v[124:127]
	v_mfma_f32_16x16x32_bf16 v[120:123], v[158:161], v[166:169], v[120:123]
	v_mfma_f32_16x16x32_bf16 v[116:119], v[150:153], v[194:197], v[116:119]
	v_mfma_f32_16x16x32_bf16 v[112:115], v[158:161], v[194:197], v[112:115]
	v_mfma_f32_16x16x32_bf16 v[108:111], v[150:153], v[202:205], v[108:111]
	v_mfma_f32_16x16x32_bf16 v[104:107], v[158:161], v[202:205], v[104:107]
	v_mfma_f32_16x16x32_bf16 v[100:103], v[150:153], v[210:213], v[100:103]
	v_mfma_f32_16x16x32_bf16 v[96:99], v[158:161], v[210:213], v[96:99]
	v_mfma_f32_16x16x32_bf16 v[124:127], v[154:157], v[170:173], v[124:127]
	v_mfma_f32_16x16x32_bf16 v[120:123], v[162:165], v[170:173], v[120:123]
	v_mfma_f32_16x16x32_bf16 v[116:119], v[154:157], v[198:201], v[116:119]
	v_mfma_f32_16x16x32_bf16 v[112:115], v[162:165], v[198:201], v[112:115]
	v_mfma_f32_16x16x32_bf16 v[108:111], v[154:157], v[206:209], v[108:111]
	v_mfma_f32_16x16x32_bf16 v[104:107], v[162:165], v[206:209], v[104:107]
	v_mfma_f32_16x16x32_bf16 v[100:103], v[154:157], v[214:217], v[100:103]
	v_mfma_f32_16x16x32_bf16 v[96:99], v[162:165], v[214:217], v[96:99]
	s_setprio 0
	s_barrier
	ds_read_b128 v[218:221], v149
	ds_read_b128 v[222:225], v149 offset:1024
	ds_read_b128 v[226:229], v149 offset:2048
	ds_read_b128 v[230:233], v149 offset:3072
	s_waitcnt vmcnt(0)
	s_barrier
	s_waitcnt lgkmcnt(0)
	s_setprio 1
	s_waitcnt lgkmcnt(0)
	v_mfma_f32_16x16x32_bf16 v[92:95], v[218:221], v[166:169], v[92:95]
	v_mfma_f32_16x16x32_bf16 v[88:91], v[226:229], v[166:169], v[88:91]
	v_mfma_f32_16x16x32_bf16 v[84:87], v[218:221], v[194:197], v[84:87]
	v_mfma_f32_16x16x32_bf16 v[80:83], v[226:229], v[194:197], v[80:83]
	v_mfma_f32_16x16x32_bf16 v[76:79], v[218:221], v[202:205], v[76:79]
	v_mfma_f32_16x16x32_bf16 v[72:75], v[226:229], v[202:205], v[72:75]
	v_mfma_f32_16x16x32_bf16 v[68:71], v[218:221], v[210:213], v[68:71]
	v_mfma_f32_16x16x32_bf16 v[64:67], v[226:229], v[210:213], v[64:67]
	v_mfma_f32_16x16x32_bf16 v[92:95], v[222:225], v[170:173], v[92:95]
	v_mfma_f32_16x16x32_bf16 v[88:91], v[230:233], v[170:173], v[88:91]
	v_mfma_f32_16x16x32_bf16 v[84:87], v[222:225], v[198:201], v[84:87]
	v_mfma_f32_16x16x32_bf16 v[80:83], v[230:233], v[198:201], v[80:83]
	v_mfma_f32_16x16x32_bf16 v[76:79], v[222:225], v[206:209], v[76:79]
	v_mfma_f32_16x16x32_bf16 v[72:75], v[230:233], v[206:209], v[72:75]
	v_mfma_f32_16x16x32_bf16 v[68:71], v[222:225], v[214:217], v[68:71]
	v_mfma_f32_16x16x32_bf16 v[64:67], v[230:233], v[214:217], v[64:67]
	s_setprio 0
	s_barrier
	ds_read_b128 v[166:169], v143 offset:49152
	ds_read_b128 v[170:173], v143 offset:50176
	ds_read_b128 v[194:197], v144 offset:49152
	ds_read_b128 v[198:201], v144 offset:50176
	ds_read_b128 v[202:205], v145 offset:49152
	ds_read_b128 v[206:209], v145 offset:50176
	ds_read_b128 v[210:213], v146 offset:49152
	ds_read_b128 v[214:217], v146 offset:50176
	s_barrier
	s_waitcnt lgkmcnt(0)
	s_setprio 1
	s_waitcnt lgkmcnt(0)
	v_mfma_f32_16x16x32_bf16 v[60:63], v[150:153], v[166:169], v[60:63]
	v_mfma_f32_16x16x32_bf16 v[56:59], v[158:161], v[166:169], v[56:59]
	v_mfma_f32_16x16x32_bf16 v[52:55], v[150:153], v[194:197], v[52:55]
	v_mfma_f32_16x16x32_bf16 v[48:51], v[158:161], v[194:197], v[48:51]
	v_mfma_f32_16x16x32_bf16 v[44:47], v[150:153], v[202:205], v[44:47]
	v_mfma_f32_16x16x32_bf16 v[40:43], v[158:161], v[202:205], v[40:43]
	v_mfma_f32_16x16x32_bf16 v[36:39], v[150:153], v[210:213], v[36:39]
	v_mfma_f32_16x16x32_bf16 v[32:35], v[158:161], v[210:213], v[32:35]
	v_mfma_f32_16x16x32_bf16 v[60:63], v[154:157], v[170:173], v[60:63]
	v_mfma_f32_16x16x32_bf16 v[56:59], v[162:165], v[170:173], v[56:59]
	v_mfma_f32_16x16x32_bf16 v[52:55], v[154:157], v[198:201], v[52:55]
	v_mfma_f32_16x16x32_bf16 v[48:51], v[162:165], v[198:201], v[48:51]
	v_mfma_f32_16x16x32_bf16 v[44:47], v[154:157], v[206:209], v[44:47]
	v_mfma_f32_16x16x32_bf16 v[40:43], v[162:165], v[206:209], v[40:43]
	v_mfma_f32_16x16x32_bf16 v[36:39], v[154:157], v[214:217], v[36:39]
	v_mfma_f32_16x16x32_bf16 v[32:35], v[162:165], v[214:217], v[32:35]
	s_setprio 0
	s_setprio 1
	v_mfma_f32_16x16x32_bf16 v[28:31], v[218:221], v[166:169], v[28:31]
	v_mfma_f32_16x16x32_bf16 v[24:27], v[226:229], v[166:169], v[24:27]
	v_mfma_f32_16x16x32_bf16 v[20:23], v[218:221], v[194:197], v[20:23]
	v_mfma_f32_16x16x32_bf16 v[16:19], v[226:229], v[194:197], v[16:19]
	v_mfma_f32_16x16x32_bf16 v[12:15], v[218:221], v[202:205], v[12:15]
	v_mfma_f32_16x16x32_bf16 v[8:11], v[226:229], v[202:205], v[8:11]
	v_mfma_f32_16x16x32_bf16 v[4:7], v[218:221], v[210:213], v[4:7]
	v_mfma_f32_16x16x32_bf16 v[0:3], v[226:229], v[210:213], v[0:3]
	v_mfma_f32_16x16x32_bf16 v[28:31], v[222:225], v[170:173], v[28:31]
	v_mfma_f32_16x16x32_bf16 v[24:27], v[230:233], v[170:173], v[24:27]
	v_mfma_f32_16x16x32_bf16 v[20:23], v[222:225], v[198:201], v[20:23]
	v_mfma_f32_16x16x32_bf16 v[16:19], v[230:233], v[198:201], v[16:19]
	v_mfma_f32_16x16x32_bf16 v[12:15], v[222:225], v[206:209], v[12:15]
	v_mfma_f32_16x16x32_bf16 v[8:11], v[230:233], v[206:209], v[8:11]
	v_mfma_f32_16x16x32_bf16 v[4:7], v[222:225], v[214:217], v[4:7]
	v_mfma_f32_16x16x32_bf16 v[0:3], v[230:233], v[214:217], v[0:3]
	s_setprio 0
	s_barrier
	s_and_saveexec_b64 s[48:49], s[40:41]
	s_cbranch_execz .LBB0_122
	s_barrier
	s_branch .LBB0_122
.Lgu_tpf:
	s_mov_b64 s[4:5], 0x780
	v_readfirstlane_b32 s22, v165
	v_lshl_add_u64 v[130:131], v[130:131], 0, s[4:5]
	s_mov_b32 m0, s22
	ds_read_b128 v[150:153], v142
	ds_read_b128 v[154:157], v142 offset:1024
	ds_read_b128 v[158:161], v142 offset:2048
	ds_read_b128 v[166:169], v142 offset:3072
	ds_read_b128 v[170:173], v143
	ds_read_b128 v[194:197], v143 offset:1024
	ds_read_b128 v[198:201], v144
	ds_read_b128 v[202:205], v144 offset:1024
	ds_read_b128 v[206:209], v145
	ds_read_b128 v[210:213], v145 offset:1024
	ds_read_b128 v[214:217], v146
	ds_read_b128 v[218:221], v146 offset:1024
	global_load_lds_dwordx4 v[130:131], off
	v_lshl_add_u64 v[130:131], v[136:137], 1, s[48:49]
	s_mov_b64 s[4:5], 0x20780
	v_readfirstlane_b32 s22, v164
	v_lshl_add_u64 v[130:131], v[130:131], 0, s[4:5]
	s_mov_b32 m0, s22
	s_nop 0
	global_load_lds_dwordx4 v[130:131], off
	v_readlane_b32 s4, v253, 57
	s_add_i32 s4, s34, s4
	s_mul_hi_i32 s5, s4, 0x30c30c31
	s_lshr_b32 s6, s5, 31
	s_ashr_i32 s5, s5, 4
	s_add_i32 s5, s5, s6
	s_mul_i32 s6, s5, 0x54
	s_sub_i32 s6, s4, s6
	s_lshl_b32 s7, s6, 8
	s_and_b32 s7, s7, 0x300
	s_lshl_b32 s6, s6, 6
	s_and_b32 s6, s6, 0xffffff00
	s_lshl_b32 s5, s5, 10
	s_or_b32 s5, s7, s5
	s_lshl_b32 s6, s6, 11
	s_lshl_b32 s5, s5, 11
	v_readlane_b32 s70, v252, 39
	v_readlane_b32 s71, v252, 40
	s_add_u32 s70, s70, s6
	s_addc_u32 s71, s71, 0
	s_add_u32 s72, s30, s5
	s_addc_u32 s73, s31, 0
	v_readfirstlane_b32 s10, v132
	s_mov_b64 s[8:9], 0x20000
	s_mov_b64 s[38:39], 0x40000
	s_barrier
	s_waitcnt lgkmcnt(0)
	s_setprio 1
	s_waitcnt lgkmcnt(0)
	v_mfma_f32_16x16x32_bf16 v[124:127], v[150:153], v[170:173], v[124:127]
	v_mfma_f32_16x16x32_bf16 v[120:123], v[158:161], v[170:173], v[120:123]
	v_mfma_f32_16x16x32_bf16 v[116:119], v[150:153], v[198:201], v[116:119]
	v_mfma_f32_16x16x32_bf16 v[112:115], v[158:161], v[198:201], v[112:115]
	v_mfma_f32_16x16x32_bf16 v[108:111], v[150:153], v[206:209], v[108:111]
	v_mfma_f32_16x16x32_bf16 v[104:107], v[158:161], v[206:209], v[104:107]
	v_mfma_f32_16x16x32_bf16 v[100:103], v[150:153], v[214:217], v[100:103]
	v_mfma_f32_16x16x32_bf16 v[96:99], v[158:161], v[214:217], v[96:99]
	v_mfma_f32_16x16x32_bf16 v[124:127], v[154:157], v[194:197], v[124:127]
	v_mfma_f32_16x16x32_bf16 v[120:123], v[166:169], v[194:197], v[120:123]
	v_mfma_f32_16x16x32_bf16 v[116:119], v[154:157], v[202:205], v[116:119]
	v_mfma_f32_16x16x32_bf16 v[112:115], v[166:169], v[202:205], v[112:115]
	v_mfma_f32_16x16x32_bf16 v[108:111], v[154:157], v[210:213], v[108:111]
	v_mfma_f32_16x16x32_bf16 v[104:107], v[166:169], v[210:213], v[104:107]
	v_mfma_f32_16x16x32_bf16 v[100:103], v[154:157], v[218:221], v[100:103]
	v_mfma_f32_16x16x32_bf16 v[96:99], v[166:169], v[218:221], v[96:99]
	s_setprio 0
	s_barrier
	ds_read_b128 v[162:165], v147
	ds_read_b128 v[222:225], v147 offset:1024
	ds_read_b128 v[226:229], v147 offset:2048
	ds_read_b128 v[230:233], v147 offset:3072
	s_barrier
	s_waitcnt lgkmcnt(0)
	s_setprio 1
	s_waitcnt lgkmcnt(0)
	v_mfma_f32_16x16x32_bf16 v[92:95], v[162:165], v[170:173], v[92:95]
	v_mfma_f32_16x16x32_bf16 v[88:91], v[226:229], v[170:173], v[88:91]
	v_mfma_f32_16x16x32_bf16 v[84:87], v[162:165], v[198:201], v[84:87]
	v_mfma_f32_16x16x32_bf16 v[80:83], v[226:229], v[198:201], v[80:83]
	v_mfma_f32_16x16x32_bf16 v[76:79], v[162:165], v[206:209], v[76:79]
	v_mfma_f32_16x16x32_bf16 v[72:75], v[226:229], v[206:209], v[72:75]
	v_mfma_f32_16x16x32_bf16 v[68:71], v[162:165], v[214:217], v[68:71]
	v_mfma_f32_16x16x32_bf16 v[64:67], v[226:229], v[214:217], v[64:67]
	v_mfma_f32_16x16x32_bf16 v[92:95], v[222:225], v[194:197], v[92:95]
	v_mfma_f32_16x16x32_bf16 v[88:91], v[230:233], v[194:197], v[88:91]
	v_mfma_f32_16x16x32_bf16 v[84:87], v[222:225], v[202:205], v[84:87]
	v_mfma_f32_16x16x32_bf16 v[80:83], v[230:233], v[202:205], v[80:83]
	v_mfma_f32_16x16x32_bf16 v[76:79], v[222:225], v[210:213], v[76:79]
	v_mfma_f32_16x16x32_bf16 v[72:75], v[230:233], v[210:213], v[72:75]
	v_mfma_f32_16x16x32_bf16 v[68:71], v[222:225], v[218:221], v[68:71]
	v_mfma_f32_16x16x32_bf16 v[64:67], v[230:233], v[218:221], v[64:67]
	s_setprio 0
	s_barrier
	ds_read_b128 v[170:173], v143 offset:16384
	ds_read_b128 v[194:197], v143 offset:17408
	ds_read_b128 v[198:201], v144 offset:16384
	ds_read_b128 v[202:205], v144 offset:17408
	ds_read_b128 v[206:209], v145 offset:16384
	ds_read_b128 v[210:213], v145 offset:17408
	ds_read_b128 v[214:217], v146 offset:16384
	ds_read_b128 v[218:221], v146 offset:17408
	s_waitcnt vmcnt(4)
	s_barrier
	s_waitcnt lgkmcnt(0)
	s_setprio 1
	s_waitcnt lgkmcnt(0)
	v_mfma_f32_16x16x32_bf16 v[60:63], v[150:153], v[170:173], v[60:63]
	v_mfma_f32_16x16x32_bf16 v[56:59], v[158:161], v[170:173], v[56:59]
	v_mfma_f32_16x16x32_bf16 v[52:55], v[150:153], v[198:201], v[52:55]
	v_mfma_f32_16x16x32_bf16 v[48:51], v[158:161], v[198:201], v[48:51]
	v_mfma_f32_16x16x32_bf16 v[44:47], v[150:153], v[206:209], v[44:47]
	v_mfma_f32_16x16x32_bf16 v[40:43], v[158:161], v[206:209], v[40:43]
	v_mfma_f32_16x16x32_bf16 v[36:39], v[150:153], v[214:217], v[36:39]
	v_mfma_f32_16x16x32_bf16 v[32:35], v[158:161], v[214:217], v[32:35]
	v_mfma_f32_16x16x32_bf16 v[60:63], v[154:157], v[194:197], v[60:63]
	v_mfma_f32_16x16x32_bf16 v[56:59], v[166:169], v[194:197], v[56:59]
	v_mfma_f32_16x16x32_bf16 v[52:55], v[154:157], v[202:205], v[52:55]
	v_mfma_f32_16x16x32_bf16 v[48:51], v[166:169], v[202:205], v[48:51]
	v_mfma_f32_16x16x32_bf16 v[44:47], v[154:157], v[210:213], v[44:47]
	v_mfma_f32_16x16x32_bf16 v[40:43], v[166:169], v[210:213], v[40:43]
	v_mfma_f32_16x16x32_bf16 v[36:39], v[154:157], v[218:221], v[36:39]
	v_mfma_f32_16x16x32_bf16 v[32:35], v[166:169], v[218:221], v[32:35]
	s_setprio 0
	s_setprio 1
	v_mfma_f32_16x16x32_bf16 v[28:31], v[162:165], v[170:173], v[28:31]
	v_mfma_f32_16x16x32_bf16 v[24:27], v[226:229], v[170:173], v[24:27]
	v_mfma_f32_16x16x32_bf16 v[20:23], v[162:165], v[198:201], v[20:23]
	v_mfma_f32_16x16x32_bf16 v[16:19], v[226:229], v[198:201], v[16:19]
	v_mfma_f32_16x16x32_bf16 v[12:15], v[162:165], v[206:209], v[12:15]
	v_mfma_f32_16x16x32_bf16 v[8:11], v[226:229], v[206:209], v[8:11]
	v_mfma_f32_16x16x32_bf16 v[4:7], v[162:165], v[214:217], v[4:7]
	v_mfma_f32_16x16x32_bf16 v[0:3], v[226:229], v[214:217], v[0:3]
	v_mfma_f32_16x16x32_bf16 v[28:31], v[222:225], v[194:197], v[28:31]
	v_mfma_f32_16x16x32_bf16 v[24:27], v[230:233], v[194:197], v[24:27]
	v_mfma_f32_16x16x32_bf16 v[20:23], v[222:225], v[202:205], v[20:23]
	v_mfma_f32_16x16x32_bf16 v[16:19], v[230:233], v[202:205], v[16:19]
	v_mfma_f32_16x16x32_bf16 v[12:15], v[222:225], v[210:213], v[12:15]
	v_mfma_f32_16x16x32_bf16 v[8:11], v[230:233], v[210:213], v[8:11]
	v_mfma_f32_16x16x32_bf16 v[4:7], v[222:225], v[218:221], v[4:7]
	v_mfma_f32_16x16x32_bf16 v[0:3], v[230:233], v[218:221], v[0:3]
	s_setprio 0
	s_barrier
	ds_read_b128 v[150:153], v148
	ds_read_b128 v[154:157], v148 offset:1024
	ds_read_b128 v[158:161], v148 offset:2048
	ds_read_b128 v[162:165], v148 offset:3072
	ds_read_b128 v[166:169], v143 offset:32768
	ds_read_b128 v[170:173], v143 offset:33792
	ds_read_b128 v[194:197], v144 offset:32768
	ds_read_b128 v[198:201], v144 offset:33792
	ds_read_b128 v[202:205], v145 offset:32768
	ds_read_b128 v[206:209], v145 offset:33792
	ds_read_b128 v[210:213], v146 offset:32768
	ds_read_b128 v[214:217], v146 offset:33792
	s_waitcnt vmcnt(2)
	s_barrier
	s_waitcnt lgkmcnt(0)
	s_setprio 1
	s_waitcnt lgkmcnt(0)
	v_mfma_f32_16x16x32_bf16 v[124:127], v[150:153], v[166:169], v[124:127]
	v_mfma_f32_16x16x32_bf16 v[120:123], v[158:161], v[166:169], v[120:123]
	v_mfma_f32_16x16x32_bf16 v[116:119], v[150:153], v[194:197], v[116:119]
	v_mfma_f32_16x16x32_bf16 v[112:115], v[158:161], v[194:197], v[112:115]
	v_mfma_f32_16x16x32_bf16 v[108:111], v[150:153], v[202:205], v[108:111]
	v_mfma_f32_16x16x32_bf16 v[104:107], v[158:161], v[202:205], v[104:107]
	v_mfma_f32_16x16x32_bf16 v[100:103], v[150:153], v[210:213], v[100:103]
	v_mfma_f32_16x16x32_bf16 v[96:99], v[158:161], v[210:213], v[96:99]
	v_mfma_f32_16x16x32_bf16 v[124:127], v[154:157], v[170:173], v[124:127]
	v_mfma_f32_16x16x32_bf16 v[120:123], v[162:165], v[170:173], v[120:123]
	v_mfma_f32_16x16x32_bf16 v[116:119], v[154:157], v[198:201], v[116:119]
	v_mfma_f32_16x16x32_bf16 v[112:115], v[162:165], v[198:201], v[112:115]
	v_mfma_f32_16x16x32_bf16 v[108:111], v[154:157], v[206:209], v[108:111]
	v_mfma_f32_16x16x32_bf16 v[104:107], v[162:165], v[206:209], v[104:107]
	v_mfma_f32_16x16x32_bf16 v[100:103], v[154:157], v[214:217], v[100:103]
	v_mfma_f32_16x16x32_bf16 v[96:99], v[162:165], v[214:217], v[96:99]
	s_setprio 0
	v_lshlrev_b64 v[234:235], 1, v[136:137]
	v_lshl_add_u64 v[236:237], s[70:71], 0, v[234:235]
	v_lshl_add_u64 v[238:239], s[72:73], 0, v[234:235]
	s_add_i32 s11, s10, 0x10000
	s_mov_b32 m0, s11
	v_lshl_add_u64 v[240:241], v[236:237], 0, s[8:9]
	global_load_lds_dwordx4 v[236:237], off
	s_add_i32 s11, s10, 0x12000
	s_mov_b32 m0, s11
	s_nop 0
	global_load_lds_dwordx4 v[240:241], off
	s_barrier
	ds_read_b128 v[218:221], v149
	ds_read_b128 v[222:225], v149 offset:1024
	ds_read_b128 v[226:229], v149 offset:2048
	ds_read_b128 v[230:233], v149 offset:3072
	s_mov_b32 m0, s10
	v_lshl_add_u64 v[240:241], v[238:239], 0, s[8:9]
	global_load_lds_dwordx4 v[238:239], off
	s_add_i32 s11, s10, 0x2000
	s_mov_b32 m0, s11
	s_nop 0
	global_load_lds_dwordx4 v[240:241], off
	s_waitcnt vmcnt(4)
	s_barrier
	s_waitcnt lgkmcnt(0)
	s_setprio 1
	s_waitcnt lgkmcnt(0)
	v_mfma_f32_16x16x32_bf16 v[92:95], v[218:221], v[166:169], v[92:95]
	v_mfma_f32_16x16x32_bf16 v[88:91], v[226:229], v[166:169], v[88:91]
	v_mfma_f32_16x16x32_bf16 v[84:87], v[218:221], v[194:197], v[84:87]
	v_mfma_f32_16x16x32_bf16 v[80:83], v[226:229], v[194:197], v[80:83]
	v_mfma_f32_16x16x32_bf16 v[76:79], v[218:221], v[202:205], v[76:79]
	v_mfma_f32_16x16x32_bf16 v[72:75], v[226:229], v[202:205], v[72:75]
	v_mfma_f32_16x16x32_bf16 v[68:71], v[218:221], v[210:213], v[68:71]
	v_mfma_f32_16x16x32_bf16 v[64:67], v[226:229], v[210:213], v[64:67]
	v_mfma_f32_16x16x32_bf16 v[92:95], v[222:225], v[170:173], v[92:95]
	v_mfma_f32_16x16x32_bf16 v[88:91], v[230:233], v[170:173], v[88:91]
	v_mfma_f32_16x16x32_bf16 v[84:87], v[222:225], v[198:201], v[84:87]
	v_mfma_f32_16x16x32_bf16 v[80:83], v[230:233], v[198:201], v[80:83]
	v_mfma_f32_16x16x32_bf16 v[76:79], v[222:225], v[206:209], v[76:79]
	v_mfma_f32_16x16x32_bf16 v[72:75], v[230:233], v[206:209], v[72:75]
	v_mfma_f32_16x16x32_bf16 v[68:71], v[222:225], v[214:217], v[68:71]
	v_mfma_f32_16x16x32_bf16 v[64:67], v[230:233], v[214:217], v[64:67]
	s_setprio 0
	s_barrier
	ds_read_b128 v[166:169], v143 offset:49152
	ds_read_b128 v[170:173], v143 offset:50176
	ds_read_b128 v[194:197], v144 offset:49152
	ds_read_b128 v[198:201], v144 offset:50176
	ds_read_b128 v[202:205], v145 offset:49152
	ds_read_b128 v[206:209], v145 offset:50176
	ds_read_b128 v[210:213], v146 offset:49152
	ds_read_b128 v[214:217], v146 offset:50176
	v_lshl_add_u64 v[236:237], v[236:237], 0, s[38:39]
	s_add_i32 s11, s10, 0x14000
	s_mov_b32 m0, s11
	v_lshl_add_u64 v[240:241], v[236:237], 0, s[8:9]
	global_load_lds_dwordx4 v[236:237], off
	s_add_i32 s11, s10, 0x16000
	s_mov_b32 m0, s11
	s_nop 0
	global_load_lds_dwordx4 v[240:241], off
	s_barrier
	s_waitcnt lgkmcnt(0)
	s_setprio 1
	s_waitcnt lgkmcnt(0)
	v_mfma_f32_16x16x32_bf16 v[60:63], v[150:153], v[166:169], v[60:63]
	v_mfma_f32_16x16x32_bf16 v[56:59], v[158:161], v[166:169], v[56:59]
	v_mfma_f32_16x16x32_bf16 v[52:55], v[150:153], v[194:197], v[52:55]
	v_mfma_f32_16x16x32_bf16 v[48:51], v[158:161], v[194:197], v[48:51]
	v_mfma_f32_16x16x32_bf16 v[44:47], v[150:153], v[202:205], v[44:47]
	v_mfma_f32_16x16x32_bf16 v[40:43], v[158:161], v[202:205], v[40:43]
	v_mfma_f32_16x16x32_bf16 v[36:39], v[150:153], v[210:213], v[36:39]
	v_mfma_f32_16x16x32_bf16 v[32:35], v[158:161], v[210:213], v[32:35]
	v_mfma_f32_16x16x32_bf16 v[60:63], v[154:157], v[170:173], v[60:63]
	v_mfma_f32_16x16x32_bf16 v[56:59], v[162:165], v[170:173], v[56:59]
	v_mfma_f32_16x16x32_bf16 v[52:55], v[154:157], v[198:201], v[52:55]
	v_mfma_f32_16x16x32_bf16 v[48:51], v[162:165], v[198:201], v[48:51]
	v_mfma_f32_16x16x32_bf16 v[44:47], v[154:157], v[206:209], v[44:47]
	v_mfma_f32_16x16x32_bf16 v[40:43], v[162:165], v[206:209], v[40:43]
	v_mfma_f32_16x16x32_bf16 v[36:39], v[154:157], v[214:217], v[36:39]
	v_mfma_f32_16x16x32_bf16 v[32:35], v[162:165], v[214:217], v[32:35]
	s_setprio 0
	s_setprio 1
	v_mfma_f32_16x16x32_bf16 v[28:31], v[218:221], v[166:169], v[28:31]
	v_mfma_f32_16x16x32_bf16 v[24:27], v[226:229], v[166:169], v[24:27]
	v_mfma_f32_16x16x32_bf16 v[20:23], v[218:221], v[194:197], v[20:23]
	v_mfma_f32_16x16x32_bf16 v[16:19], v[226:229], v[194:197], v[16:19]
	v_mfma_f32_16x16x32_bf16 v[12:15], v[218:221], v[202:205], v[12:15]
	v_mfma_f32_16x16x32_bf16 v[8:11], v[226:229], v[202:205], v[8:11]
	v_mfma_f32_16x16x32_bf16 v[4:7], v[218:221], v[210:213], v[4:7]
	v_mfma_f32_16x16x32_bf16 v[0:3], v[226:229], v[210:213], v[0:3]
	v_mfma_f32_16x16x32_bf16 v[28:31], v[222:225], v[170:173], v[28:31]
	v_mfma_f32_16x16x32_bf16 v[24:27], v[230:233], v[170:173], v[24:27]
	v_mfma_f32_16x16x32_bf16 v[20:23], v[222:225], v[198:201], v[20:23]
	v_mfma_f32_16x16x32_bf16 v[16:19], v[230:233], v[198:201], v[16:19]
	v_mfma_f32_16x16x32_bf16 v[12:15], v[222:225], v[206:209], v[12:15]
	v_mfma_f32_16x16x32_bf16 v[8:11], v[230:233], v[206:209], v[8:11]
	v_mfma_f32_16x16x32_bf16 v[4:7], v[222:225], v[214:217], v[4:7]
	v_mfma_f32_16x16x32_bf16 v[0:3], v[230:233], v[214:217], v[0:3]
	s_setprio 0
	v_lshl_add_u64 v[238:239], v[238:239], 0, s[38:39]
	s_add_i32 s11, s10, 0x4000
	s_mov_b32 m0, s11
	v_lshl_add_u64 v[240:241], v[238:239], 0, s[8:9]
	global_load_lds_dwordx4 v[238:239], off
	s_add_i32 s11, s10, 0x6000
	s_mov_b32 m0, s11
	s_nop 0
	global_load_lds_dwordx4 v[240:241], off
	s_barrier
	s_and_saveexec_b64 s[48:49], s[40:41]
	s_cbranch_execz .LBB0_122
	s_barrier
	s_branch .LBB0_122
.Lgu_hdr2:
	v_readlane_b32 s4, v253, 57
	s_add_i32 s22, s76, s4
	s_mul_hi_i32 s23, s22, 0x30c30c31
	s_lshr_b32 s34, s23, 31
	s_ashr_i32 s23, s23, 4
	s_add_i32 s23, s23, s34
	s_mul_i32 s34, s23, 0x54
	s_sub_i32 s34, s22, s34
	s_lshl_b32 s22, s34, 8
	s_lshl_b32 s34, s34, 6
	s_and_b32 s44, s34, 0xffffff00
	s_and_b32 s22, s22, 0x300
	s_lshl_b32 s23, s23, 10
	s_ashr_i32 s45, s44, 31
	s_or_b32 s42, s22, s23
	s_lshl_b64 s[70:71], s[44:45], 11
	v_readlane_b32 s4, v252, 39
	v_readlane_b32 s5, v252, 40
	s_add_u32 s34, s4, s70
	s_addc_u32 s35, s5, s71
	v_lshlrev_b64 v[6:7], 1, v[136:137]
	v_add_u32_e32 v150, s75, v132
	v_lshl_add_u64 v[0:1], s[34:35], 0, v[6:7]
	v_readfirstlane_b32 s34, v150
	v_add_u32_e32 v151, 0x2000, v150
	s_mov_b32 m0, s34
	v_readfirstlane_b32 s34, v151
	s_ashr_i32 s43, s42, 31
	s_mov_b32 m0, s34
	s_lshl_b64 s[34:35], s[42:43], 11
	s_mov_b64 s[6:7], 0x20000
	s_add_u32 s34, s30, s34
	v_lshl_add_u64 v[2:3], v[0:1], 0, s[6:7]
	s_addc_u32 s35, s31, s35
	v_add_u32_e32 v152, 0, v132
	v_lshl_add_u64 v[2:3], s[34:35], 0, v[6:7]
	v_readfirstlane_b32 s34, v152
	v_add_u32_e32 v153, 0x2000, v152
	s_mov_b32 m0, s34
	v_readfirstlane_b32 s34, v153
	s_mov_b32 m0, s34
	s_or_b32 s34, s44, 0x80
	s_ashr_i32 s35, s34, 31
	s_lshl_b64 s[34:35], s[34:35], 11
	s_add_u32 s34, s4, s34
	v_readlane_b32 s4, v254, 8
	v_lshl_add_u64 v[4:5], v[2:3], 0, s[6:7]
	s_addc_u32 s35, s5, s35
	v_add_u32_e32 v154, s4, v132
	v_lshl_add_u64 v[4:5], s[34:35], 0, v[6:7]
	v_readfirstlane_b32 s34, v154
	v_add_u32_e32 v155, 0x2000, v154
	s_mov_b32 m0, s34
	v_readfirstlane_b32 s34, v155
	s_mov_b32 m0, s34
	s_or_b32 s34, s42, 0x80
	s_ashr_i32 s35, s34, 31
	s_lshl_b64 s[34:35], s[34:35], 11
	s_add_u32 s48, s30, s34
	v_add_u32_e32 v156, 0x4000, v152
	v_lshl_add_u64 v[8:9], v[4:5], 0, s[6:7]
	s_addc_u32 s49, s31, s35
	v_readfirstlane_b32 s34, v156
	v_add_u32_e32 v157, 0x6000, v152
	v_lshl_add_u64 v[130:131], s[48:49], 0, v[6:7]
	s_mov_b32 m0, s34
	v_readfirstlane_b32 s34, v157
	v_lshl_add_u64 v[6:7], v[130:131], 0, s[6:7]
	s_mov_b32 m0, s34
	s_nop 0
	s_and_saveexec_b64 s[72:73], vcc
	s_cbranch_execz .Lgu_h2_125
	s_barrier
.Lgu_h2_125:
	s_or_b64 exec, exec, s[72:73]
	v_readlane_b32 s4, v254, 9
	s_mov_b64 s[6:7], 0x80
	v_lshl_add_u64 v[6:7], v[0:1], 0, s[6:7]
	v_add_u32_e32 v158, s4, v132
	v_add_u32_e32 v159, 0x2000, v158
	v_readfirstlane_b32 s34, v158
	s_mov_b32 m0, s34
	s_mov_b64 s[8:9], 0x20080
	v_readfirstlane_b32 s34, v159
	v_add_u32_e32 v160, 0x8000, v152
	s_waitcnt vmcnt(20)
	s_barrier
	global_load_lds_dwordx4 v[6:7], off
	v_lshl_add_u64 v[0:1], v[0:1], 0, s[8:9]
	s_mov_b32 m0, s34
	v_readfirstlane_b32 s34, v160
	v_add_u32_e32 v161, 0xa000, v152
	v_readlane_b32 s4, v254, 10
	global_load_lds_dwordx4 v[0:1], off
	v_lshl_add_u64 v[0:1], v[2:3], 0, s[6:7]
	s_mov_b32 m0, s34
	v_readfirstlane_b32 s34, v161
	v_add_u32_e32 v162, s4, v132
	global_load_lds_dwordx4 v[0:1], off
	v_lshl_add_u64 v[0:1], v[2:3], 0, s[8:9]
	s_mov_b32 m0, s34
	v_readfirstlane_b32 s34, v162
	v_add_u32_e32 v163, 0x2000, v162
	global_load_lds_dwordx4 v[0:1], off
	v_lshl_add_u64 v[0:1], v[4:5], 0, s[6:7]
	s_mov_b32 m0, s34
	v_readfirstlane_b32 s34, v163
	global_load_lds_dwordx4 v[0:1], off
	v_lshl_add_u64 v[0:1], v[4:5], 0, s[8:9]
	s_mov_b32 m0, s34
	s_add_u32 s70, s92, s70
	global_load_lds_dwordx4 v[0:1], off
	s_addc_u32 s71, s93, s71
	s_add_i32 s22, s23, s22
	s_ashr_i32 s23, s22, 31
	s_waitcnt vmcnt(22)
	s_lshl_b64 s[22:23], s[22:23], 11
	s_add_u32 s72, s92, s22
	v_mov_b32_e32 v0, 0
	s_addc_u32 s73, s93, s23
	s_mov_b32 s22, -2
	s_branch .Lgu_join
